# v56 + DF row-sum chain as scalar v_add pairs (no s_nop), d=3 V reads via immediate offsets
# speedup vs baseline: 1.0071x; 1.0025x over previous
.LBB0_567:
	s_waitcnt lgkmcnt(3)
	v_mfma_f32_32x32x16_bf16 v[32:47], v[124:127], v[172:175], v[32:47]
	ds_read_b128 v[188:191], v247 offset:9216
	ds_read_b128 v[184:187], v247 offset:9248
	ds_read_b128 v[180:183], v247 offset:9280
	ds_read_b128 v[176:179], v247 offset:9312
	v_exp_f32_e32 v200, v96
	v_exp_f32_e32 v201, v97
	v_exp_f32_e32 v202, v98
	v_exp_f32_e32 v203, v99
	v_cvt_pk_bf16_f32 v192, v200, v201
	v_cvt_pk_bf16_f32 v193, v202, v203
	s_waitcnt lgkmcnt(6)
	v_mfma_f32_32x32x16_bf16 v[32:47], v[120:123], v[168:171], v[32:47]
	v_exp_f32_e32 v124, v100
	v_exp_f32_e32 v125, v101
	v_exp_f32_e32 v126, v102
	v_exp_f32_e32 v127, v103
	v_cvt_pk_bf16_f32 v194, v124, v125
	v_cvt_pk_bf16_f32 v195, v126, v127
	s_waitcnt lgkmcnt(5)
	v_mfma_f32_32x32x16_bf16 v[32:47], v[116:119], v[164:167], v[32:47]
	v_exp_f32_e32 v120, v104
	v_exp_f32_e32 v121, v105
	v_exp_f32_e32 v122, v106
	v_exp_f32_e32 v123, v107
	v_cvt_pk_bf16_f32 v196, v120, v121
	v_cvt_pk_bf16_f32 v197, v122, v123
	s_waitcnt lgkmcnt(4)
	v_mfma_f32_32x32x16_bf16 v[32:47], v[112:115], v[160:163], v[32:47]
	v_exp_f32_e32 v116, v108
	v_exp_f32_e32 v117, v109
	v_exp_f32_e32 v118, v110
	v_exp_f32_e32 v119, v111
	v_cvt_pk_bf16_f32 v198, v116, v117
	v_cvt_pk_bf16_f32 v199, v118, v119
	v_add_f32_e32 v112, v202, v200
	v_add_f32_e32 v113, v203, v201
	s_waitcnt lgkmcnt(3)
	v_mfma_f32_32x32x16_bf16 v[16:31], v[188:191], v[172:175], v[16:31]
	v_add_f32_e32 v112, v124, v112
	v_add_f32_e32 v113, v125, v113
	ds_read_b128 v[96:99], v247 offset:13824
	ds_read_b128 v[100:103], v247 offset:13856
	ds_read_b128 v[104:107], v247 offset:13888
	ds_read_b128 v[108:111], v247 offset:13920
	v_add_f32_e32 v112, v126, v112
	v_add_f32_e32 v113, v127, v113
	v_exp_f32_e32 v80, v80
	v_exp_f32_e32 v81, v81
	v_add_f32_e32 v112, v120, v112
	v_add_f32_e32 v113, v121, v113
	v_cvt_pk_bf16_f32 v200, v80, v81
	v_add_f32_e32 v112, v122, v112
	v_add_f32_e32 v113, v123, v113
	v_add_f32_e32 v112, v116, v112
	v_add_f32_e32 v113, v117, v113
	v_add_f32_e32 v112, v118, v112
	v_add_f32_e32 v113, v119, v113
	v_add_f32_e32 v112, v80, v112
	v_add_f32_e32 v113, v81, v113
	s_waitcnt lgkmcnt(6)
	v_mfma_f32_32x32x16_bf16 v[16:31], v[184:187], v[168:171], v[16:31]
	v_exp_f32_e32 v80, v82
	v_exp_f32_e32 v81, v83
	v_add_f32_e32 v82, v80, v112
	v_cvt_pk_bf16_f32 v201, v80, v81
	v_add_f32_e32 v83, v81, v113
	s_waitcnt lgkmcnt(5)
	v_mfma_f32_32x32x16_bf16 v[16:31], v[180:183], v[164:167], v[16:31]
	v_exp_f32_e32 v80, v84
	v_exp_f32_e32 v81, v85
	v_add_f32_e32 v82, v80, v82
	v_cvt_pk_bf16_f32 v202, v80, v81
	v_add_f32_e32 v83, v81, v83
	s_waitcnt lgkmcnt(4)
	v_mfma_f32_32x32x16_bf16 v[16:31], v[176:179], v[160:163], v[16:31]
	v_exp_f32_e32 v80, v86
	v_exp_f32_e32 v81, v87
	v_add_f32_e32 v82, v80, v82
	v_cvt_pk_bf16_f32 v203, v80, v81
	v_add_f32_e32 v83, v81, v83
	s_waitcnt lgkmcnt(3)
	v_mfma_f32_32x32x16_bf16 v[0:15], v[96:99], v[172:175], v[0:15]
	v_exp_f32_e32 v80, v88
	v_exp_f32_e32 v81, v89
	v_add_f32_e32 v82, v80, v82
	v_cvt_pk_bf16_f32 v204, v80, v81
	v_add_f32_e32 v83, v81, v83
	s_waitcnt lgkmcnt(2)
	v_mfma_f32_32x32x16_bf16 v[0:15], v[100:103], v[168:171], v[0:15]
	v_exp_f32_e32 v80, v90
	v_exp_f32_e32 v81, v91
	v_add_f32_e32 v82, v80, v82
	v_cvt_pk_bf16_f32 v205, v80, v81
	v_add_f32_e32 v83, v81, v83
	s_waitcnt lgkmcnt(1)
	v_mfma_f32_32x32x16_bf16 v[0:15], v[104:107], v[164:167], v[0:15]
	v_exp_f32_e32 v80, v92
	v_exp_f32_e32 v81, v93
	v_add_f32_e32 v82, v80, v82
	v_cvt_pk_bf16_f32 v206, v80, v81
	v_add_f32_e32 v83, v81, v83
	s_waitcnt lgkmcnt(0)
	v_mfma_f32_32x32x16_bf16 v[0:15], v[108:111], v[160:163], v[0:15]
	v_exp_f32_e32 v80, v94
	v_exp_f32_e32 v81, v95
	v_add_f32_e32 v82, v80, v82
	v_cvt_pk_bf16_f32 v207, v80, v81
	v_add_f32_e32 v83, v81, v83
	v_add_f32_e32 v252, v82, v83
	v_fmac_f32_e32 v252, v223, v224
	v_mov_b32_e32 v163, v207
	v_mov_b32_e32 v162, v206
	v_mov_b32_e32 v161, v205
	v_mov_b32_e32 v160, v204
	v_mov_b32_e32 v167, v203
	v_mov_b32_e32 v166, v202
	v_mov_b32_e32 v165, v201
	v_mov_b32_e32 v164, v200
	v_mov_b32_e32 v171, v199
	v_mov_b32_e32 v170, v198
	v_mov_b32_e32 v169, v197
	v_mov_b32_e32 v168, v196
	v_mov_b32_e32 v175, v195
	v_mov_b32_e32 v174, v194
	v_mov_b32_e32 v173, v193
	v_mov_b32_e32 v172, v192
	s_branch .LBB0_570
